# row-norm phases (P1, P8): next row's loads prefetched into spare registers during the current row's reduce/store; counted loop-top wait (stores not waited)
# baseline (speedup 1.0000x reference)
; __device__ __forceinline__ float wave_sum(float v) {
; #pragma unroll
;     for (int o = 1; o < 64; o <<= 1) v += __shfl_xor(v, o);
;     return v;
;     for (int r = 0; r < rpw; ++r) {
;         const int row = row0 + wave * rpw + r;
;         const f32x4* xr = (const f32x4*)(X + (size_t)row * DM) + lane;
;         f32x4 v[8]; float ss = 0.f;
; #pragma unroll
;         for (int j = 0; j < 8; ++j) { v[j] = __builtin_nontemporal_load(&xr[64 * j]); ss += (v[j].x * v[j].x + v[j].y * v[j].y) + (v[j].z * v[j].z + v[j].w * v[j].w); }
;         ss = wave_sum(ss);
.LBB0_168:
	s_andn2_b64 vcc, exec, s[0:1]
	s_cbranch_vccnz .LBB0_153
	v_and_b32_e32 v0, 64, v60
	v_add_u32_e32 v0, 64, v0
	v_xor_b32_e32 v1, 1, v60
	v_cmp_lt_i32_e32 vcc, v1, v0
	s_ashr_i32 s21, s20, 31
	s_lshl_b64 s[0:1], s[20:21], 13
	v_cndmask_b32_e32 v1, v60, v1, vcc
	v_lshlrev_b32_e32 v61, 2, v1
	v_xor_b32_e32 v1, 2, v60
	v_cmp_lt_i32_e32 vcc, v1, v0
	v_lshl_add_u64 v[50:51], v[48:49], 0, s[0:1]
	s_lshl_b64 s[0:1], s[20:21], 12
	v_cndmask_b32_e32 v1, v60, v1, vcc
	v_lshlrev_b32_e32 v62, 2, v1
	v_xor_b32_e32 v1, 4, v60
	v_cmp_lt_i32_e32 vcc, v1, v0
	v_lshl_add_u64 v[52:53], v[44:45], 0, s[0:1]
	s_mov_b64 s[8:9], 0
	v_cndmask_b32_e32 v1, v60, v1, vcc
	v_lshlrev_b32_e32 v63, 2, v1
	v_xor_b32_e32 v1, 8, v60
	v_cmp_lt_i32_e32 vcc, v1, v0
	s_nop 1
	v_cndmask_b32_e32 v1, v60, v1, vcc
	v_lshlrev_b32_e32 v64, 2, v1
	v_xor_b32_e32 v1, 16, v60
	v_cmp_lt_i32_e32 vcc, v1, v0
	s_nop 1
	v_cndmask_b32_e32 v1, v60, v1, vcc
	v_lshlrev_b32_e32 v65, 2, v1
	v_xor_b32_e32 v1, 32, v60
	v_cmp_lt_i32_e32 vcc, v1, v0
	s_nop 1
	v_cndmask_b32_e32 v0, v60, v1, vcc
	v_lshlrev_b32_e32 v66, 2, v0
	global_load_dwordx4 v[108:111], v[50:51], off offset:-4096 nt
	global_load_dwordx4 v[104:107], v[50:51], off offset:-3072 nt
	global_load_dwordx4 v[116:119], v[50:51], off offset:-2048 nt
	global_load_dwordx4 v[120:123], v[50:51], off nt
	global_load_dwordx4 v[124:127], v[50:51], off offset:-1024 nt
	global_load_dwordx4 v[128:131], v[50:51], off offset:1024 nt
	global_load_dwordx4 v[112:115], v[50:51], off offset:3072 nt
	global_load_dwordx4 v[132:135], v[50:51], off offset:2048 nt
	s_mov_b64 s[0:1], 0x2000
	v_lshl_add_u64 v[50:51], v[50:51], 0, s[0:1]
	s_waitcnt vmcnt(0)
	s_branch .Lrow_body_170
.LBB0_170:
	s_waitcnt vmcnt(8)
.Lrow_body_170:
	v_mov_b64_e32 v[0:1], v[104:105]
	v_mov_b64_e32 v[2:3], v[106:107]
	v_mov_b64_e32 v[4:5], v[108:109]
	v_mov_b64_e32 v[6:7], v[110:111]
	v_mov_b64_e32 v[8:9], v[112:113]
	v_mov_b64_e32 v[10:11], v[114:115]
	v_mov_b64_e32 v[12:13], v[116:117]
	v_mov_b64_e32 v[14:15], v[118:119]
	v_mov_b64_e32 v[16:17], v[120:121]
	v_mov_b64_e32 v[18:19], v[122:123]
	v_mov_b64_e32 v[20:21], v[124:125]
	v_mov_b64_e32 v[22:23], v[126:127]
	v_mov_b64_e32 v[24:25], v[128:129]
	v_mov_b64_e32 v[26:27], v[130:131]
	v_mov_b64_e32 v[28:29], v[132:133]
	v_mov_b64_e32 v[30:31], v[134:135]
	s_cmpk_eq_u32 s8, 0x7000
	s_cbranch_scc1 .Lrow_nopf_170
	global_load_dwordx4 v[108:111], v[50:51], off offset:-4096 nt
	global_load_dwordx4 v[104:107], v[50:51], off offset:-3072 nt
	global_load_dwordx4 v[116:119], v[50:51], off offset:-2048 nt
	global_load_dwordx4 v[120:123], v[50:51], off nt
	global_load_dwordx4 v[124:127], v[50:51], off offset:-1024 nt
	global_load_dwordx4 v[128:131], v[50:51], off offset:1024 nt
	global_load_dwordx4 v[112:115], v[50:51], off offset:3072 nt
	global_load_dwordx4 v[132:135], v[50:51], off offset:2048 nt
; #define LAS __attribute__((address_space(3)))
; __device__ __forceinline__ unsigned cvt_pk_bf16(float lo, float hi) { unsigned r; asm volatile("v_cvt_pk_bf16_f32 %0, %1, %2" : "=v"(r) : "v"(lo), "v"(hi)); return r; }
;     for (int r = 0; r < rpw; ++r) {
;         const int row = row0 + wave * rpw + r;
;         const f32x4* xr = (const f32x4*)(X + (size_t)row * DM) + lane;
;         f32x4 v[8]; float ss = 0.f;
; #pragma unroll
;         for (int j = 0; j < 8; ++j) { v[j] = __builtin_nontemporal_load(&xr[64 * j]); ss += (v[j].x * v[j].x + v[j].y * v[j].y) + (v[j].z * v[j].z + v[j].w * v[j].w); }
;         ss = wave_sum(ss);
;         const float rstd = rsqrtf(ss * (1.0f / DM) + EPS);
;         u32x2* op = (u32x2*)(OUT + (size_t)row * DM) + lane;
; #pragma unroll
;         for (int j = 0; j < 8; ++j) { const int col = 4 * lane + 256 * j; const f32x4 a = *(const LAS f32x4*)(mA + col), s = *(const LAS f32x4*)(mS + col);
;             const f32x4 ov = v[j] * rstd * a + s; u32x2 w; w.x = cvt_pk_bf16(ov.x, ov.y); w.y = cvt_pk_bf16(ov.z, ov.w); op[64 * j] = w; }
;     }
.Lrow_nopf_170:
	v_lshl_add_u64 v[68:69], v[52:53], 0, s[8:9]
	s_mov_b32 s18, 0x6c00000
	v_add_co_u32_e32 v68, vcc, s18, v68
	ds_read_b128 v[32:35], v54
	ds_read_b128 v[36:39], v54 offset:8192
	v_addc_co_u32_e32 v69, vcc, 0, v69, vcc
	s_add_u32 s8, s8, 0x1000
	s_mov_b64 s[0:1], 0x2000
	s_addc_u32 s9, s9, 0
	v_lshl_add_u64 v[50:51], v[50:51], 0, s[0:1]
	s_cmpk_eq_u32 s8, 0x8000
	s_nop 0
	v_mov_b32_e32 v72, v5
	s_nop 0
	v_mov_b32_e32 v73, v1
	v_mov_b32_e32 v76, v7
	v_mov_b32_e32 v77, v3
	v_mov_b32_e32 v70, v4
	v_mov_b32_e32 v71, v0
	v_mov_b32_e32 v74, v6
	v_mov_b32_e32 v75, v2
	s_nop 0
	v_pk_mul_f32 v[78:79], v[14:15], v[14:15]
	v_pk_mul_f32 v[80:81], v[12:13], v[12:13]
	v_pk_mul_f32 v[72:73], v[72:73], v[72:73]
	v_pk_mul_f32 v[76:77], v[76:77], v[76:77]
	v_pk_mov_b32 v[94:95], v[80:81], v[78:79] op_sel:[1,0]
	v_mov_b32_e32 v81, v79
	v_pk_fma_f32 v[70:71], v[70:71], v[70:71], v[72:73]
	v_pk_fma_f32 v[72:73], v[74:75], v[74:75], v[76:77]
	s_nop 0
	v_mul_f32_e32 v82, v21, v21
	v_mul_f32_e32 v84, v23, v23
	v_pk_add_f32 v[74:75], v[94:95], v[80:81]
	v_pk_add_f32 v[70:71], v[70:71], v[72:73]
	v_mul_f32_e32 v67, v16, v16
	v_mul_f32_e32 v93, v17, v17
	v_mul_f32_e32 v96, v18, v18
	v_mul_f32_e32 v97, v19, v19
	v_pk_fma_f32 v[78:79], v[20:21], v[20:21], v[82:83] op_sel_hi:[1,1,0]
	v_pk_fma_f32 v[82:83], v[22:23], v[22:23], v[84:85] op_sel_hi:[1,1,0]
	v_pk_add_f32 v[72:73], v[74:75], v[74:75] op_sel:[0,1] op_sel_hi:[1,0]
	v_pk_add_f32 v[70:71], v[70:71], v[70:71] op_sel:[0,1] op_sel_hi:[1,0]
	s_nop 0
	v_pk_mul_f32 v[86:87], v[26:27], v[26:27]
	v_pk_mul_f32 v[88:89], v[24:25], v[24:25]
	v_mov_b32_e32 v79, v96
	v_mov_b32_e32 v83, v97
	v_mov_b32_e32 v73, v93
	v_mov_b32_e32 v71, v67
	v_pk_mov_b32 v[84:85], v[88:89], v[86:87] op_sel:[1,0]
	v_mov_b32_e32 v89, v87
	v_pk_add_f32 v[74:75], v[78:79], v[82:83]
	v_pk_add_f32 v[70:71], v[70:71], v[72:73]
	s_nop 0
	v_mul_f32_e32 v90, v29, v29
	v_mul_f32_e32 v92, v31, v31
	v_pk_add_f32 v[76:77], v[84:85], v[88:89]
	v_pk_add_f32 v[70:71], v[70:71], v[74:75]
	v_mul_f32_e32 v98, v8, v8
	v_mul_f32_e32 v99, v9, v9
	v_mul_f32_e32 v100, v10, v10
	v_mul_f32_e32 v101, v11, v11
	v_pk_fma_f32 v[86:87], v[28:29], v[28:29], v[90:91] op_sel_hi:[1,1,0]
	v_pk_fma_f32 v[90:91], v[30:31], v[30:31], v[92:93] op_sel_hi:[1,1,0]
	v_pk_add_f32 v[76:77], v[76:77], v[76:77] op_sel:[0,1] op_sel_hi:[1,0]
	v_pk_add_f32 v[70:71], v[70:71], v[70:71] op_sel:[0,1] op_sel_hi:[1,0]
	v_mov_b32_e32 v87, v100
	v_mov_b32_e32 v91, v101
	v_mov_b32_e32 v77, v99
	v_mov_b32_e32 v71, v98
	v_pk_add_f32 v[78:79], v[86:87], v[90:91]
	v_pk_add_f32 v[70:71], v[70:71], v[76:77]
	s_nop 0
	v_pk_add_f32 v[70:71], v[70:71], v[78:79]
	s_nop 0
	v_add_f32_e32 v67, v70, v71
	ds_bpermute_b32 v70, v61, v67
	s_waitcnt lgkmcnt(0)
	v_add_f32_e32 v67, v67, v70
	ds_bpermute_b32 v70, v62, v67
	s_waitcnt lgkmcnt(0)
	v_add_f32_e32 v67, v67, v70
	ds_bpermute_b32 v70, v63, v67
	s_waitcnt lgkmcnt(0)
	v_add_f32_e32 v67, v67, v70
	ds_bpermute_b32 v70, v64, v67
	s_waitcnt lgkmcnt(0)
	v_add_f32_e32 v67, v67, v70
	ds_bpermute_b32 v70, v65, v67
	s_waitcnt lgkmcnt(0)
	v_add_f32_e32 v67, v67, v70
	ds_bpermute_b32 v70, v66, v67
	s_waitcnt lgkmcnt(0)
	v_add_f32_e32 v67, v67, v70
	v_fmamk_f32 v67, v67, 0x3a000000, v59
	v_mul_f32_e32 v70, 0x4b800000, v67
	v_cmp_gt_f32_e32 vcc, s72, v67
	s_nop 1
	v_cndmask_b32_e32 v67, v67, v70, vcc
	v_rsq_f32_e32 v67, v67
	s_nop 0
	v_mul_f32_e32 v70, 0x45800000, v67
	v_cndmask_b32_e32 v70, v67, v70, vcc
	v_pk_mul_f32 v[4:5], v[4:5], v[70:71] op_sel_hi:[1,0]
	v_pk_mul_f32 v[6:7], v[6:7], v[70:71] op_sel_hi:[1,0]
	v_pk_mul_f32 v[72:73], v[0:1], v[70:71] op_sel_hi:[1,0]
	v_pk_mul_f32 v[74:75], v[2:3], v[70:71] op_sel_hi:[1,0]
	v_pk_fma_f32 v[0:1], v[34:35], v[6:7], v[38:39]
	v_pk_fma_f32 v[2:3], v[32:33], v[4:5], v[36:37]
	v_pk_mul_f32 v[12:13], v[12:13], v[70:71] op_sel_hi:[1,0]
	v_cvt_pk_bf16_f32 v32, v2, v3
	v_cvt_pk_bf16_f32 v33, v0, v1
	ds_read_b128 v[0:3], v54 offset:1024
	ds_read_b128 v[4:7], v54 offset:9216
	global_store_dwordx2 v[68:69], v[32:33], off
	v_pk_mul_f32 v[14:15], v[14:15], v[70:71] op_sel_hi:[1,0]
	v_pk_mul_f32 v[20:21], v[20:21], v[70:71] op_sel_hi:[1,0]
	v_pk_mul_f32 v[22:23], v[22:23], v[70:71] op_sel_hi:[1,0]
	s_waitcnt lgkmcnt(0)
	v_pk_fma_f32 v[2:3], v[2:3], v[74:75], v[6:7]
	v_pk_fma_f32 v[0:1], v[0:1], v[72:73], v[4:5]
	v_pk_mul_f32 v[16:17], v[16:17], v[70:71] op_sel_hi:[1,0]
	v_cvt_pk_bf16_f32 v32, v0, v1
	v_cvt_pk_bf16_f32 v33, v2, v3
	ds_read_b128 v[0:3], v54 offset:2048
	ds_read_b128 v[4:7], v54 offset:10240
	global_store_dwordx2 v[68:69], v[32:33], off offset:512
	v_pk_mul_f32 v[18:19], v[18:19], v[70:71] op_sel_hi:[1,0]
	v_pk_mul_f32 v[24:25], v[24:25], v[70:71] op_sel_hi:[1,0]
	v_pk_mul_f32 v[26:27], v[26:27], v[70:71] op_sel_hi:[1,0]
	s_waitcnt lgkmcnt(0)
	v_pk_fma_f32 v[2:3], v[2:3], v[14:15], v[6:7]
	v_pk_fma_f32 v[0:1], v[0:1], v[12:13], v[4:5]
	v_pk_mul_f32 v[28:29], v[28:29], v[70:71] op_sel_hi:[1,0]
	v_cvt_pk_bf16_f32 v12, v0, v1
	v_cvt_pk_bf16_f32 v13, v2, v3
	ds_read_b128 v[0:3], v54 offset:3072
	ds_read_b128 v[4:7], v54 offset:11264
	global_store_dwordx2 v[68:69], v[12:13], off offset:1024
	v_pk_mul_f32 v[30:31], v[30:31], v[70:71] op_sel_hi:[1,0]
	v_pk_mul_f32 v[8:9], v[8:9], v[70:71] op_sel_hi:[1,0]
	v_pk_mul_f32 v[10:11], v[10:11], v[70:71] op_sel_hi:[1,0]
	s_waitcnt lgkmcnt(0)
	v_pk_fma_f32 v[2:3], v[22:23], v[2:3], v[6:7]
	v_pk_fma_f32 v[0:1], v[20:21], v[0:1], v[4:5]
	s_nop 0
	v_cvt_pk_bf16_f32 v12, v0, v1
	v_cvt_pk_bf16_f32 v13, v2, v3
	ds_read_b128 v[0:3], v54 offset:4096
	ds_read_b128 v[4:7], v54 offset:12288
	global_store_dwordx2 v[68:69], v[12:13], off offset:1536
	s_waitcnt lgkmcnt(0)
	v_pk_fma_f32 v[2:3], v[18:19], v[2:3], v[6:7]
	v_pk_fma_f32 v[0:1], v[16:17], v[0:1], v[4:5]
	s_nop 0
	v_cvt_pk_bf16_f32 v12, v0, v1
	v_cvt_pk_bf16_f32 v13, v2, v3
	ds_read_b128 v[0:3], v54 offset:5120
	ds_read_b128 v[4:7], v54 offset:13312
	global_store_dwordx2 v[68:69], v[12:13], off offset:2048
	s_waitcnt lgkmcnt(0)
	v_pk_fma_f32 v[2:3], v[26:27], v[2:3], v[6:7]
	v_pk_fma_f32 v[0:1], v[24:25], v[0:1], v[4:5]
	s_nop 0
	v_cvt_pk_bf16_f32 v12, v0, v1
	v_cvt_pk_bf16_f32 v13, v2, v3
	ds_read_b128 v[0:3], v54 offset:6144
	ds_read_b128 v[4:7], v54 offset:14336
	global_store_dwordx2 v[68:69], v[12:13], off offset:2560
	s_waitcnt lgkmcnt(0)
	v_pk_fma_f32 v[2:3], v[30:31], v[2:3], v[6:7]
	v_pk_fma_f32 v[0:1], v[28:29], v[0:1], v[4:5]
	s_nop 0
	v_cvt_pk_bf16_f32 v12, v0, v1
	v_cvt_pk_bf16_f32 v13, v2, v3
	ds_read_b128 v[0:3], v54 offset:7168
	ds_read_b128 v[4:7], v54 offset:15360
	global_store_dwordx2 v[68:69], v[12:13], off offset:3072
	s_waitcnt lgkmcnt(0)
	v_pk_fma_f32 v[0:1], v[8:9], v[0:1], v[4:5]
	v_pk_fma_f32 v[2:3], v[10:11], v[2:3], v[6:7]
	v_cvt_pk_bf16_f32 v0, v0, v1
	s_nop 0
	v_cvt_pk_bf16_f32 v1, v2, v3
	global_store_dwordx2 v[68:69], v[0:1], off offset:3584
	s_cbranch_scc0 .LBB0_170
	s_branch .LBB0_153

; #define LAS __attribute__((address_space(3)))
; #define PHASE_IDS() int tid = threadIdx.x; asm volatile("" : "+v"(tid)); const int lane = tid & 63, wave = __builtin_amdgcn_readfirstlane(tid >> 6); (void)lane; (void)wave
;     for (int r = 0; r < rpw; ++r) {
;         const int row = row0 + wave * rpw + r;
;         const f32x4* xr = (const f32x4*)(X + (size_t)row * DM) + lane;
;         f32x4 v[8]; float ss = 0.f;
; #pragma unroll
;         for (int j = 0; j < 8; ++j) { v[j] = __builtin_nontemporal_load(&xr[64 * j]); ss += (v[j].x * v[j].x + v[j].y * v[j].y) + (v[j].z * v[j].z + v[j].w * v[j].w); }
; __global__ void __launch_bounds__(NTHREADS, 2) fwd_kernel(Args a) {
;     ...
;     if (IN(8)) for (int rep = 0; rep < NREP(8); ++rep) { if (rep) cg::this_grid().sync(); PHASE_IDS();
;         LAS float* mA = (LAS float*)ldsl; LAS float* mS = mA + DM; const float* g2 = a.in[I_N2G];
;         for (int q = bx; q < 256; q += G) {
;             const int cond = q >> 6;
;             __syncthreads();
;             for (int col = tid; col < DM; col += NTHREADS) { mA[col] = g2[col] * (1.0f + MOD[(size_t)cond * ADAW + 4 * DM + col]); mS[col] = MOD[(size_t)cond * ADAW + 3 * DM + col]; }
;             __syncthreads();
;             norm_chunk(a.out, H2, q * 64, mA, mS, wave, lane);
.LBB0_901:
	s_or_b64 exec, exec, s[28:29]
	s_ashr_i32 s21, s20, 31
	s_lshl_b64 s[0:1], s[20:21], 13
	v_lshl_add_u64 v[46:47], v[42:43], 0, s[0:1]
	s_lshl_b64 s[0:1], s[20:21], 12
	v_lshl_add_u64 v[48:49], v[44:45], 0, s[0:1]
	s_mov_b64 s[28:29], 0
	s_waitcnt lgkmcnt(0)
	s_barrier
	global_load_dwordx4 v[100:103], v[46:47], off offset:-4096 nt
	global_load_dwordx4 v[96:99], v[46:47], off offset:-3072 nt
	global_load_dwordx4 v[108:111], v[46:47], off offset:-2048 nt
	global_load_dwordx4 v[112:115], v[46:47], off nt
	global_load_dwordx4 v[116:119], v[46:47], off offset:-1024 nt
	global_load_dwordx4 v[120:123], v[46:47], off offset:1024 nt
	global_load_dwordx4 v[104:107], v[46:47], off offset:3072 nt
	global_load_dwordx4 v[124:127], v[46:47], off offset:2048 nt
	v_lshl_add_u64 v[46:47], v[46:47], 0, s[26:27]
	s_waitcnt vmcnt(0)
	s_branch .Lrow_body_902

;     for (int r = 0; r < rpw; ++r) {
;         const int row = row0 + wave * rpw + r;
;         const f32x4* xr = (const f32x4*)(X + (size_t)row * DM) + lane;
;         f32x4 v[8]; float ss = 0.f;
; #pragma unroll
;         for (int j = 0; j < 8; ++j) { v[j] = __builtin_nontemporal_load(&xr[64 * j]); ss += (v[j].x * v[j].x + v[j].y * v[j].y) + (v[j].z * v[j].z + v[j].w * v[j].w); }
.Lrow_body_902:
	v_mov_b64_e32 v[0:1], v[96:97]
	v_mov_b64_e32 v[2:3], v[98:99]
	v_mov_b64_e32 v[4:5], v[100:101]
	v_mov_b64_e32 v[6:7], v[102:103]
	v_mov_b64_e32 v[8:9], v[104:105]
	v_mov_b64_e32 v[10:11], v[106:107]
	v_mov_b64_e32 v[12:13], v[108:109]
	v_mov_b64_e32 v[14:15], v[110:111]
	v_mov_b64_e32 v[16:17], v[112:113]
	v_mov_b64_e32 v[18:19], v[114:115]
	v_mov_b64_e32 v[20:21], v[116:117]
	v_mov_b64_e32 v[22:23], v[118:119]
	v_mov_b64_e32 v[24:25], v[120:121]
	v_mov_b64_e32 v[26:27], v[122:123]
	v_mov_b64_e32 v[28:29], v[124:125]
	v_mov_b64_e32 v[30:31], v[126:127]
	s_cmpk_eq_u32 s28, 0x7000
	s_cbranch_scc1 .Lrow_nopf_902
	global_load_dwordx4 v[100:103], v[46:47], off offset:-4096 nt
	global_load_dwordx4 v[96:99], v[46:47], off offset:-3072 nt
	global_load_dwordx4 v[108:111], v[46:47], off offset:-2048 nt
	global_load_dwordx4 v[112:115], v[46:47], off nt
	global_load_dwordx4 v[116:119], v[46:47], off offset:-1024 nt
	global_load_dwordx4 v[120:123], v[46:47], off offset:1024 nt
	global_load_dwordx4 v[104:107], v[46:47], off offset:3072 nt
	global_load_dwordx4 v[124:127], v[46:47], off offset:2048 nt
; #define LAS __attribute__((address_space(3)))
; __device__ __forceinline__ unsigned cvt_pk_bf16(float lo, float hi) { unsigned r; asm volatile("v_cvt_pk_bf16_f32 %0, %1, %2" : "=v"(r) : "v"(lo), "v"(hi)); return r; }
;     for (int r = 0; r < rpw; ++r) {
;         const int row = row0 + wave * rpw + r;
;         const f32x4* xr = (const f32x4*)(X + (size_t)row * DM) + lane;
;         f32x4 v[8]; float ss = 0.f;
; #pragma unroll
;         for (int j = 0; j < 8; ++j) { v[j] = __builtin_nontemporal_load(&xr[64 * j]); ss += (v[j].x * v[j].x + v[j].y * v[j].y) + (v[j].z * v[j].z + v[j].w * v[j].w); }
;         ss = wave_sum(ss);
;         const float rstd = rsqrtf(ss * (1.0f / DM) + EPS);
;         u32x2* op = (u32x2*)(OUT + (size_t)row * DM) + lane;
; #pragma unroll
;         for (int j = 0; j < 8; ++j) { const int col = 4 * lane + 256 * j; const f32x4 a = *(const LAS f32x4*)(mA + col), s = *(const LAS f32x4*)(mS + col);
;             const f32x4 ov = v[j] * rstd * a + s; u32x2 w; w.x = cvt_pk_bf16(ov.x, ov.y); w.y = cvt_pk_bf16(ov.z, ov.w); op[64 * j] = w; }
;     }
; __global__ void __launch_bounds__(NTHREADS, 2) fwd_kernel(Args a) {
;     ...
;         for (int q = bx; q < 256; q += G) {
;             const int cond = q >> 6;
;             __syncthreads();
;             for (int col = tid; col < DM; col += NTHREADS) { mA[col] = g2[col] * (1.0f + MOD[(size_t)cond * ADAW + 4 * DM + col]); mS[col] = MOD[(size_t)cond * ADAW + 3 * DM + col]; }
;             __syncthreads();
;             norm_chunk(a.out, H2, q * 64, mA, mS, wave, lane);
;         }
.Lrow_nopf_902:
	v_lshl_add_u64 v[58:59], v[48:49], 0, s[28:29]
	v_add_co_u32_e32 v58, vcc, s42, v58
	ds_read_b128 v[32:35], v50
	ds_read_b128 v[36:39], v50 offset:8192
	v_addc_co_u32_e32 v59, vcc, 0, v59, vcc
	s_add_u32 s28, s28, 0x1000
	s_addc_u32 s29, s29, 0
	v_lshl_add_u64 v[46:47], v[46:47], 0, s[26:27]
	s_cmpk_lg_u32 s28, 0x8000
	s_nop 0
	v_mov_b32_e32 v62, v5
	s_nop 0
	v_mov_b32_e32 v63, v1
	v_mov_b32_e32 v66, v7
	v_mov_b32_e32 v67, v3
	v_mov_b32_e32 v60, v4
	v_mov_b32_e32 v61, v0
	v_mov_b32_e32 v64, v6
	v_mov_b32_e32 v65, v2
	s_nop 0
	v_pk_mul_f32 v[68:69], v[14:15], v[14:15]
	v_pk_mul_f32 v[70:71], v[12:13], v[12:13]
	v_pk_mul_f32 v[62:63], v[62:63], v[62:63]
	v_pk_mul_f32 v[66:67], v[66:67], v[66:67]
	v_pk_mov_b32 v[84:85], v[70:71], v[68:69] op_sel:[1,0]
	v_mov_b32_e32 v71, v69
	v_pk_fma_f32 v[60:61], v[60:61], v[60:61], v[62:63]
	v_pk_fma_f32 v[62:63], v[64:65], v[64:65], v[66:67]
	s_nop 0
	v_mul_f32_e32 v72, v21, v21
	v_mul_f32_e32 v74, v23, v23
	v_pk_add_f32 v[64:65], v[84:85], v[70:71]
	v_pk_add_f32 v[60:61], v[60:61], v[62:63]
	v_mul_f32_e32 v57, v16, v16
	v_mul_f32_e32 v83, v17, v17
	v_mul_f32_e32 v86, v18, v18
	v_mul_f32_e32 v87, v19, v19
	v_pk_fma_f32 v[68:69], v[20:21], v[20:21], v[72:73] op_sel_hi:[1,1,0]
	v_pk_fma_f32 v[72:73], v[22:23], v[22:23], v[74:75] op_sel_hi:[1,1,0]
	v_pk_add_f32 v[62:63], v[64:65], v[64:65] op_sel:[0,1] op_sel_hi:[1,0]
	v_pk_add_f32 v[60:61], v[60:61], v[60:61] op_sel:[0,1] op_sel_hi:[1,0]
	s_nop 0
	v_pk_mul_f32 v[76:77], v[26:27], v[26:27]
	v_pk_mul_f32 v[78:79], v[24:25], v[24:25]
	v_mov_b32_e32 v69, v86
	v_mov_b32_e32 v73, v87
	v_mov_b32_e32 v63, v83
	v_mov_b32_e32 v61, v57
	v_pk_mov_b32 v[74:75], v[78:79], v[76:77] op_sel:[1,0]
	v_mov_b32_e32 v79, v77
	v_pk_add_f32 v[64:65], v[68:69], v[72:73]
	v_pk_add_f32 v[60:61], v[60:61], v[62:63]
	s_nop 0
	v_mul_f32_e32 v80, v29, v29
	v_mul_f32_e32 v82, v31, v31
	v_pk_add_f32 v[66:67], v[74:75], v[78:79]
	v_pk_add_f32 v[60:61], v[60:61], v[64:65]
	v_mul_f32_e32 v88, v8, v8
	v_mul_f32_e32 v89, v9, v9
	v_mul_f32_e32 v90, v10, v10
	v_mul_f32_e32 v91, v11, v11
	v_pk_fma_f32 v[76:77], v[28:29], v[28:29], v[80:81] op_sel_hi:[1,1,0]
	v_pk_fma_f32 v[80:81], v[30:31], v[30:31], v[82:83] op_sel_hi:[1,1,0]
	v_pk_add_f32 v[66:67], v[66:67], v[66:67] op_sel:[0,1] op_sel_hi:[1,0]
	v_pk_add_f32 v[60:61], v[60:61], v[60:61] op_sel:[0,1] op_sel_hi:[1,0]
	v_mov_b32_e32 v77, v90
	v_mov_b32_e32 v81, v91
	v_mov_b32_e32 v67, v89
	v_mov_b32_e32 v61, v88
	v_pk_add_f32 v[68:69], v[76:77], v[80:81]
	v_pk_add_f32 v[60:61], v[60:61], v[66:67]
	s_nop 0
	v_pk_add_f32 v[60:61], v[60:61], v[68:69]
	s_nop 0
	v_add_f32_e32 v57, v60, v61
	ds_bpermute_b32 v60, v162, v57
	s_waitcnt lgkmcnt(0)
	v_add_f32_e32 v57, v57, v60
	ds_bpermute_b32 v60, v163, v57
	s_waitcnt lgkmcnt(0)
	v_add_f32_e32 v57, v57, v60
	ds_bpermute_b32 v60, v164, v57
	s_waitcnt lgkmcnt(0)
	v_add_f32_e32 v57, v57, v60
	ds_bpermute_b32 v60, v165, v57
	s_waitcnt lgkmcnt(0)
	v_add_f32_e32 v57, v57, v60
	ds_bpermute_b32 v60, v166, v57
	s_waitcnt lgkmcnt(0)
	v_add_f32_e32 v57, v57, v60
	ds_bpermute_b32 v60, v167, v57
	s_waitcnt lgkmcnt(0)
	v_add_f32_e32 v57, v57, v60
	v_fmamk_f32 v57, v57, 0x3a000000, v56
	v_mul_f32_e32 v60, 0x4b800000, v57
	v_cmp_gt_f32_e32 vcc, s41, v57
	s_nop 1
	v_cndmask_b32_e32 v57, v57, v60, vcc
	v_rsq_f32_e32 v57, v57
	s_nop 0
	v_mul_f32_e32 v60, 0x45800000, v57
	v_cndmask_b32_e32 v60, v57, v60, vcc
	v_pk_mul_f32 v[4:5], v[4:5], v[60:61] op_sel_hi:[1,0]
	v_pk_mul_f32 v[6:7], v[6:7], v[60:61] op_sel_hi:[1,0]
	v_pk_mul_f32 v[62:63], v[0:1], v[60:61] op_sel_hi:[1,0]
	v_pk_mul_f32 v[64:65], v[2:3], v[60:61] op_sel_hi:[1,0]
	v_pk_fma_f32 v[0:1], v[34:35], v[6:7], v[38:39]
	v_pk_fma_f32 v[2:3], v[32:33], v[4:5], v[36:37]
	v_pk_mul_f32 v[12:13], v[12:13], v[60:61] op_sel_hi:[1,0]
	v_cvt_pk_bf16_f32 v32, v2, v3
	v_cvt_pk_bf16_f32 v33, v0, v1
	ds_read_b128 v[0:3], v50 offset:1024
	ds_read_b128 v[4:7], v50 offset:9216
	global_store_dwordx2 v[58:59], v[32:33], off
	v_pk_mul_f32 v[14:15], v[14:15], v[60:61] op_sel_hi:[1,0]
	v_pk_mul_f32 v[20:21], v[20:21], v[60:61] op_sel_hi:[1,0]
	v_pk_mul_f32 v[22:23], v[22:23], v[60:61] op_sel_hi:[1,0]
	s_waitcnt lgkmcnt(0)
	v_pk_fma_f32 v[2:3], v[2:3], v[64:65], v[6:7]
	v_pk_fma_f32 v[0:1], v[0:1], v[62:63], v[4:5]
	v_pk_mul_f32 v[16:17], v[16:17], v[60:61] op_sel_hi:[1,0]
	v_cvt_pk_bf16_f32 v32, v0, v1
	v_cvt_pk_bf16_f32 v33, v2, v3
	ds_read_b128 v[0:3], v50 offset:2048
	ds_read_b128 v[4:7], v50 offset:10240
	global_store_dwordx2 v[58:59], v[32:33], off offset:512
	v_pk_mul_f32 v[18:19], v[18:19], v[60:61] op_sel_hi:[1,0]
	v_pk_mul_f32 v[24:25], v[24:25], v[60:61] op_sel_hi:[1,0]
	v_pk_mul_f32 v[26:27], v[26:27], v[60:61] op_sel_hi:[1,0]
	s_waitcnt lgkmcnt(0)
	v_pk_fma_f32 v[2:3], v[2:3], v[14:15], v[6:7]
	v_pk_fma_f32 v[0:1], v[0:1], v[12:13], v[4:5]
	v_pk_mul_f32 v[28:29], v[28:29], v[60:61] op_sel_hi:[1,0]
	v_cvt_pk_bf16_f32 v12, v0, v1
	v_cvt_pk_bf16_f32 v13, v2, v3
	ds_read_b128 v[0:3], v50 offset:3072
	ds_read_b128 v[4:7], v50 offset:11264
	global_store_dwordx2 v[58:59], v[12:13], off offset:1024
	v_pk_mul_f32 v[30:31], v[30:31], v[60:61] op_sel_hi:[1,0]
	v_pk_mul_f32 v[8:9], v[8:9], v[60:61] op_sel_hi:[1,0]
	v_pk_mul_f32 v[10:11], v[10:11], v[60:61] op_sel_hi:[1,0]
	s_waitcnt lgkmcnt(0)
	v_pk_fma_f32 v[2:3], v[22:23], v[2:3], v[6:7]
	v_pk_fma_f32 v[0:1], v[20:21], v[0:1], v[4:5]
	s_nop 0
	v_cvt_pk_bf16_f32 v12, v0, v1
	v_cvt_pk_bf16_f32 v13, v2, v3
	ds_read_b128 v[0:3], v50 offset:4096
	ds_read_b128 v[4:7], v50 offset:12288
	global_store_dwordx2 v[58:59], v[12:13], off offset:1536
	s_waitcnt lgkmcnt(0)
	v_pk_fma_f32 v[2:3], v[18:19], v[2:3], v[6:7]
	v_pk_fma_f32 v[0:1], v[16:17], v[0:1], v[4:5]
	s_nop 0
	v_cvt_pk_bf16_f32 v12, v0, v1
	v_cvt_pk_bf16_f32 v13, v2, v3
	ds_read_b128 v[0:3], v50 offset:5120
	ds_read_b128 v[4:7], v50 offset:13312
	global_store_dwordx2 v[58:59], v[12:13], off offset:2048
	s_waitcnt lgkmcnt(0)
	v_pk_fma_f32 v[2:3], v[26:27], v[2:3], v[6:7]
	v_pk_fma_f32 v[0:1], v[24:25], v[0:1], v[4:5]
	s_nop 0
	v_cvt_pk_bf16_f32 v12, v0, v1
	v_cvt_pk_bf16_f32 v13, v2, v3
	ds_read_b128 v[0:3], v50 offset:6144
	ds_read_b128 v[4:7], v50 offset:14336
	global_store_dwordx2 v[58:59], v[12:13], off offset:2560
	s_waitcnt lgkmcnt(0)
	v_pk_fma_f32 v[2:3], v[30:31], v[2:3], v[6:7]
	v_pk_fma_f32 v[0:1], v[28:29], v[0:1], v[4:5]
	s_nop 0
	v_cvt_pk_bf16_f32 v12, v0, v1
	v_cvt_pk_bf16_f32 v13, v2, v3
	ds_read_b128 v[0:3], v50 offset:7168
	ds_read_b128 v[4:7], v50 offset:15360
	global_store_dwordx2 v[58:59], v[12:13], off offset:3072
	s_waitcnt lgkmcnt(0)
	v_pk_fma_f32 v[0:1], v[8:9], v[0:1], v[4:5]
	v_pk_fma_f32 v[2:3], v[10:11], v[2:3], v[6:7]
	v_cvt_pk_bf16_f32 v0, v0, v1
	s_nop 0
	v_cvt_pk_bf16_f32 v1, v2, v3
	global_store_dwordx2 v[58:59], v[0:1], off offset:3584
	s_cbranch_scc1 .LBB0_902
	s_add_i32 s43, s43, s15
	s_add_i32 s20, s20, s35
	s_cmpk_gt_i32 s43, 0xff
	s_cbranch_scc0 .LBB0_886
